# c21: dense attention row-sum adds as scalar v_add_f32 pairs instead of packed v_pk_add_f32 (bit-identical)
# baseline (speedup 1.0000x reference)
; #define ATA_LOAD(RK, RV, t) do { const size_t tb = (size_t)(t) * 64 * 128; RK[0] = *(const u32x4*)(Kb + tb + goff0); RV[0] = *(const u32x4*)(Vb + tb + goff0); } while (0)
; #define ATA_STORE(RK, RV, st) do { unsigned char* sb_ = smem + (st) * ATA_STAGE; *(u32x4*)(sb_ + ko0) = RK[0]; *(u32x4*)(sb_ + vo0) = RV[0]; } while (0)
; __device__ void attn_a_item(const Params& p, int item, int l, unsigned char* smem) {
;     ...
;     __syncthreads();
;     ATA_LOAD(rkA, rvA, 0); ATA_LOAD(rkB, rvB, 1);
;     ATA_STORE(rkA, rvA, 0);
;     ATA_LOAD(rkA, rvA, 2);
;     __syncthreads();
;     for (int kt = 0; kt < NT; kt += 2) {
;         ATA_COMPUTE(0);
;         ATA_STORE(rkB, rvB, 1);
;         if (kt + 3 < NT) ATA_LOAD(rkB, rvB, kt + 3);
;         __syncthreads();
;         ATA_COMPUTE(1);
;         if (kt + 2 < NT) { ATA_STORE(rkA, rvA, 0); if (kt + 4 < NT) ATA_LOAD(rkA, rvA, kt + 4); }
;         __syncthreads();
.LBB0_846:
	v_add_f32_e32 v116, v116, v150
	v_add_f32_e32 v117, v117, v151
	v_add_f32_e32 v118, v118, v148
	v_add_f32_e32 v119, v119, v149
	v_add_f32_e32 v116, v136, v116
	v_add_f32_e32 v117, v137, v117
	v_add_f32_e32 v118, v146, v118
	v_add_f32_e32 v119, v147, v119
	v_add_f32_e32 v116, v142, v116
	v_add_f32_e32 v117, v143, v117
	v_add_f32_e32 v118, v144, v118
	v_add_f32_e32 v119, v145, v119
	v_add_f32_e32 v116, v128, v116
	v_add_f32_e32 v117, v129, v117
	v_add_f32_e32 v118, v140, v118
	v_add_f32_e32 v119, v141, v119
	v_add_f32_e32 v116, v134, v116
	v_add_f32_e32 v117, v135, v117
	v_add_f32_e32 v118, v138, v118
	v_add_f32_e32 v119, v139, v119
	v_add_f32_e32 v116, v122, v116
	v_add_f32_e32 v117, v123, v117
	v_add_f32_e32 v118, v132, v118
	v_add_f32_e32 v119, v133, v119
	v_add_f32_e32 v116, v126, v116
	v_add_f32_e32 v117, v127, v117
	v_add_f32_e32 v118, v130, v118
	v_add_f32_e32 v119, v131, v119
	v_add_f32_e32 v116, v120, v116
	v_add_f32_e32 v117, v121, v117
	v_add_f32_e32 v118, v124, v118
	v_add_f32_e32 v119, v125, v119
	v_add_f32_e32 v64, v116, v64
	v_add_f32_e32 v65, v117, v65
	v_add_f32_e32 v66, v118, v66
	v_add_f32_e32 v67, v119, v67
	v_add_f32_e32 v48, v48, v64
	v_add_f32_e32 v49, v49, v65
	v_add_f32_e32 v50, v50, v66
	v_add_f32_e32 v51, v51, v67
	v_add_f32_e32 v48, v68, v48
	v_add_f32_e32 v49, v69, v49
	v_add_f32_e32 v50, v70, v50
	v_add_f32_e32 v51, v71, v51
	v_add_f32_e32 v48, v52, v48
	v_add_f32_e32 v49, v53, v49
	v_add_f32_e32 v50, v54, v50
	v_add_f32_e32 v51, v55, v51
	v_add_f32_e32 v48, v72, v48
	v_add_f32_e32 v49, v73, v49
	v_add_f32_e32 v50, v74, v50
	v_add_f32_e32 v51, v75, v51
	v_add_f32_e32 v48, v56, v48
	v_add_f32_e32 v49, v57, v49
	v_add_f32_e32 v50, v58, v50
	v_add_f32_e32 v51, v59, v51
	v_add_f32_e32 v48, v76, v48
	v_add_f32_e32 v49, v77, v49
	v_add_f32_e32 v50, v78, v50
	v_add_f32_e32 v51, v79, v51
	v_add_f32_e32 v116, v60, v48
	v_add_f32_e32 v117, v61, v49
	v_add_f32_e32 v118, v62, v50
	v_add_f32_e32 v119, v63, v51
	s_add_i32 s12, s12, 2
	v_lshl_add_u64 v[114:115], v[114:115], 0, s[14:15]
	s_and_b64 vcc, exec, s[44:45]
	s_waitcnt lgkmcnt(0)
	s_barrier
	s_cbranch_vccnz .LBB0_852
